# attention loops: trim over-padded s_nop before row-max (24->10 states), drop 8 v_mov_b64 by using negm as SrcC directly, drop m0 save/restore around LDS-DMA
# speedup vs baseline: 1.3361x; 1.3361x over previous
; __device__ __forceinline__ void glds16(const void* gsrc, unsigned lds_dst) { unsigned keep;
;     asm volatile("s_mov_b32 %0, m0\n\ts_mov_b32 m0, %2\n\ts_nop 0\n\tglobal_load_lds_dwordx4 %1, off\n\ts_mov_b32 m0, %0" : "=&s"(keep) : "v"(gsrc), "s"(lds_dst) : "memory"); }
.LBB0_683:
	s_add_i32 s9, s56, 2
	s_min_u32 s16, s9, s52
	s_and_b32 s9, s57, 0xc000
	s_lshl_b64 s[10:11], s[16:17], 14
	s_add_i32 s9, s9, s53
	s_add_i32 s9, s9, 0
	v_lshl_add_u64 v[2:3], v[178:179], 0, s[10:11]
	s_mov_b32 m0, s9
	s_nop 0
	global_load_lds_dwordx4 v[2:3], off
	v_lshl_add_u64 v[2:3], v[2:3], 0, s[22:23]
	s_add_i32 s58, s9, 0x2000
	s_mov_b32 m0, s58
	s_nop 0
	global_load_lds_dwordx4 v[2:3], off
	s_add_i32 s16, s9, 0x10000
	v_lshl_add_u64 v[2:3], v[180:181], 0, s[10:11]
	s_mov_b32 m0, s16
	s_nop 0
	global_load_lds_dwordx4 v[2:3], off
	v_lshl_add_u64 v[2:3], v[2:3], 0, s[22:23]
	s_add_i32 s9, s9, 0x12000
	s_mov_b32 m0, s9
	s_nop 0
	global_load_lds_dwordx4 v[2:3], off
	s_waitcnt vmcnt(4) lgkmcnt(0)
	s_barrier
	s_add_i32 s56, s56, 1
	s_addk_i32 s57, 0x4000
	s_add_i32 s55, s55, 64
	s_cmp_eq_u32 s50, s56
	s_cbranch_scc1 .LBB0_693

; __device__ __forceinline__ int crow(int r, int hi) { return (r & 3) + 8 * (r >> 2) + 4 * hi; }
; __device__ __forceinline__ float xhalf_max(float v) { auto rr = __builtin_amdgcn_permlane32_swap(__float_as_uint(v), __float_as_uint(v), false, false); return fmaxf(__uint_as_float(rr[0]), __uint_as_float(rr[1])); }
; __device__ __forceinline__ float max3a(float a, float b, float c) { float r; asm("v_max3_f32 %0, %1, %2, %3" : "=v"(r) : "v"(a), "v"(b), "v"(c)); return r; }
; __device__ __forceinline__ void att_qs(bf16x8 (&pn)[4], f32x16 (&o)[4], f32x16& osum, f32x16& negm, const bf16x8 (&qf)[4], float& m_hat, ...
;     __builtin_amdgcn_s_setprio(1);
;     f32x16 c0, c1;
;     bf16x8 kf[4];
;     ...
;     kf[0] = ATT_KREAD(0); kf[1] = ATT_KREAD(1); kf[2] = ATT_KREAD(2); kf[3] = ATT_KREAD(3);
;     __builtin_amdgcn_sched_barrier(0);
; #pragma unroll
;     for (int i = 0; i < 8; ++i) {
;         if (i == 0) c0 = __builtin_amdgcn_mfma_f32_32x32x16_bf16(kf[0], qf[0], negm, 0, 0, 0);
;         else if (i == 1) c1 = __builtin_amdgcn_mfma_f32_32x32x16_bf16(kf[1], qf[0], negm, 0, 0, 0);
;         else if ((i & 1) == 0) c0 = __builtin_amdgcn_mfma_f32_32x32x16_bf16(kf[i & 3], qf[i >> 1], c0, 0, 0, 0);
;         else c1 = __builtin_amdgcn_mfma_f32_32x32x16_bf16(kf[i & 3], qf[i >> 1], c1, 0, 0, 0);
;         if (i + 4 < 8) kf[i & 3] = ATT_KREAD(i + 4);
;         __builtin_amdgcn_sched_barrier(0);
;     }
;     ...
;     if (near) {
; #pragma unroll
;         for (int r = 0; r < 16; ++r) { int i0 = lutbase + crow(r, hi), i1 = i0 + 32; i0 = i0 < 0 ? 0 : (i0 > 255 ? 255 : i0); i1 = i1 < 0 ? 0 : (i1 > 255 ? 255 : i1); c0[r] += lut[i0]; c1[r] += lut[i1]; }
;     }
;     if (first_tile) {
; #pragma unroll
;         for (int r = 0; r < 16; ++r) { if (crow(r, hi) >= NMETA) c0[r] = -INFINITY; c1[r] = -INFINITY; }
;     }
;     asm volatile("s_nop 15\n\ts_nop 7" : "+v"(c0), "+v"(c1));
;     float rm;
;     { float a = max3a(c0[0], c0[1], c0[2]), b = max3a(c1[0], c1[1], c1[2]);
; #pragma unroll
;       for (int r = 3; r < 15; r += 2) { a = max3a(a, c0[r], c0[r + 1]); b = max3a(b, c1[r], c1[r + 1]); }
;       rm = max3a(a, b, c0[15]); rm = max3a(rm, c1[15], c1[15]); }
;     rm = xhalf_max(rm);
.LBB0_686:
	s_cmp_gt_u32 s56, s54
	s_cbranch_scc1 .LBB0_683
	s_add_i32 s9, s57, 0xffff8000
	s_and_b32 s9, s9, 0xc000
	s_cmpk_lt_i32 s55, 0xffa6
	s_setprio 1
	v_add_u32_e32 v0, s9, v177
	ds_read_b128 v[2:5], v0
	ds_read_b128 v[6:9], v0 offset:512
	ds_read_b128 v[10:13], v0 offset:2048
	ds_read_b128 v[228:231], v0 offset:2560
	s_waitcnt lgkmcnt(3)
	v_mfma_f32_32x32x16_bf16 v[130:145], v[2:5], v[146:149], v[98:113]
	ds_read_b128 v[232:235], v0 offset:4096
	ds_read_b128 v[2:5], v0 offset:4608
	s_waitcnt lgkmcnt(4)
	v_mfma_f32_32x32x16_bf16 v[114:129], v[6:9], v[146:149], v[98:113]
	s_waitcnt lgkmcnt(3)
	v_mfma_f32_32x32x16_bf16 v[130:145], v[10:13], v[150:153], v[130:145]
	ds_read_b128 v[6:9], v0 offset:6144
	s_waitcnt lgkmcnt(3)
	v_mfma_f32_32x32x16_bf16 v[114:129], v[228:231], v[150:153], v[114:129]
	ds_read_b128 v[10:13], v0 offset:6656
	s_waitcnt lgkmcnt(3)
	v_mfma_f32_32x32x16_bf16 v[130:145], v[232:235], v[154:157], v[130:145]
	s_waitcnt lgkmcnt(2)
	v_mfma_f32_32x32x16_bf16 v[114:129], v[2:5], v[154:157], v[114:129]
	s_waitcnt lgkmcnt(1)
	v_mfma_f32_32x32x16_bf16 v[130:145], v[6:9], v[158:161], v[130:145]
	s_waitcnt lgkmcnt(0)
	v_mfma_f32_32x32x16_bf16 v[114:129], v[10:13], v[158:161], v[114:129]
	s_cbranch_scc1 .LBB0_689
	v_add_u32_e32 v0, s55, v219
	v_add_u32_e32 v2, 0x41, v0
	v_med3_i32 v3, v2, 0, v222
	v_med3_i32 v2, v2, s38, v223
	v_lshl_add_u32 v4, v2, 2, s37
	v_add_u32_e32 v2, 0x42, v0
	v_med3_i32 v5, v2, 0, v222
	v_med3_i32 v2, v2, s38, v223
	v_lshl_add_u32 v6, v2, 2, s37
	v_add_u32_e32 v2, 0x43, v0
	v_med3_i32 v7, v2, 0, v222
	v_med3_i32 v2, v2, s38, v223
	v_lshl_add_u32 v8, v2, 2, s37
	v_add_u32_e32 v2, 0x44, v0
	v_med3_i32 v9, v2, 0, v222
	v_med3_i32 v2, v2, s38, v223
	v_lshl_add_u32 v3, v3, 2, s37
	v_lshl_add_u32 v5, v5, 2, s37
	v_lshl_add_u32 v7, v7, 2, s37
	v_lshl_add_u32 v9, v9, 2, s37
	v_lshl_add_u32 v10, v2, 2, s37
	ds_read_b32 v2, v3
	ds_read_b32 v4, v4 offset:128
	ds_read_b32 v3, v5
	ds_read_b32 v5, v6 offset:128
	ds_read_b32 v6, v7
	ds_read_b32 v8, v8 offset:128
	ds_read_b32 v7, v9
	ds_read_b32 v9, v10 offset:128
	v_add_u32_e32 v10, 0x49, v0
	v_med3_i32 v11, v10, 0, v222
	v_med3_i32 v10, v10, s38, v223
	v_lshl_add_u32 v12, v10, 2, s37
	v_add_u32_e32 v10, 0x4a, v0
	v_med3_i32 v13, v10, 0, v222
	v_med3_i32 v10, v10, s38, v223
	v_lshl_add_u32 v14, v10, 2, s37
	v_add_u32_e32 v10, 0x4b, v0
	v_med3_i32 v15, v10, 0, v222
	v_med3_i32 v10, v10, s38, v223
	v_add_u32_e32 v231, 0x52, v0
	v_lshl_add_u32 v227, v10, 2, s37
	v_add_u32_e32 v10, 0x4c, v0
	v_med3_i32 v232, v231, 0, v222
	v_med3_i32 v231, v231, s38, v223
	v_med3_i32 v228, v10, 0, v222
	v_lshl_add_u32 v234, v231, 2, s37
	v_add_u32_e32 v231, 0x53, v0
	v_lshl_add_u32 v11, v11, 2, s37
	v_lshl_add_u32 v13, v13, 2, s37
	v_lshl_add_u32 v15, v15, 2, s37
	v_med3_i32 v10, v10, s38, v223
	v_lshl_add_u32 v229, v228, 2, s37
	v_lshl_add_u32 v233, v232, 2, s37
	v_med3_i32 v232, v231, 0, v222
	v_med3_i32 v231, v231, s38, v223
	v_lshl_add_u32 v230, v10, 2, s37
	ds_read_b32 v10, v11
	ds_read_b32 v12, v12 offset:128
	ds_read_b32 v11, v13
	ds_read_b32 v13, v14 offset:128
	ds_read_b32 v14, v15
	ds_read_b32 v228, v227 offset:128
	ds_read_b32 v15, v229
	ds_read_b32 v229, v230 offset:128
	v_add_u32_e32 v227, 0x51, v0
	v_lshl_add_u32 v236, v231, 2, s37
	v_add_u32_e32 v231, 0x54, v0
	v_add_u32_e32 v239, 0x5a, v0
	v_med3_i32 v230, v227, 0, v222
	v_med3_i32 v227, v227, s38, v223
	v_lshl_add_u32 v235, v232, 2, s37
	v_med3_i32 v232, v231, 0, v222
	v_med3_i32 v240, v239, 0, v222
	v_med3_i32 v239, v239, s38, v223
	v_lshl_add_u32 v230, v230, 2, s37
	v_lshl_add_u32 v227, v227, 2, s37
	v_med3_i32 v231, v231, s38, v223
	v_lshl_add_u32 v237, v232, 2, s37
	v_lshl_add_u32 v244, v239, 2, s37
	v_add_u32_e32 v239, 0x5b, v0
	v_lshl_add_u32 v238, v231, 2, s37
	ds_read_b32 v230, v230
	ds_read_b32 v232, v227 offset:128
	ds_read_b32 v231, v233
	ds_read_b32 v233, v234 offset:128
	ds_read_b32 v234, v235
	ds_read_b32 v236, v236 offset:128
	ds_read_b32 v235, v237
	ds_read_b32 v237, v238 offset:128
	v_add_u32_e32 v227, 0x59, v0
	v_lshl_add_u32 v241, v240, 2, s37
	v_med3_i32 v240, v239, 0, v222
	v_med3_i32 v239, v239, s38, v223
	v_add_u32_e32 v0, 0x5c, v0
	v_med3_i32 v238, v227, 0, v222
	v_lshl_add_u32 v245, v239, 2, s37
	v_med3_i32 v239, v0, 0, v222
	v_med3_i32 v227, v227, s38, v223
	v_lshl_add_u32 v238, v238, 2, s37
	v_lshl_add_u32 v242, v240, 2, s37
	v_med3_i32 v0, v0, s38, v223
	v_lshl_add_u32 v239, v239, 2, s37
	v_lshl_add_u32 v227, v227, 2, s37
	v_lshl_add_u32 v0, v0, 2, s37
	ds_read_b32 v238, v238
	ds_read_b32 v240, v227 offset:128
	ds_read_b32 v242, v242
	ds_read_b32 v243, v239
	ds_read_b32 v239, v241
	ds_read_b32 v241, v244 offset:128
	ds_read_b32 v244, v245 offset:128
	ds_read_b32 v245, v0 offset:128
	s_waitcnt lgkmcnt(4)
	v_pk_add_f32 v[144:145], v[144:145], v[242:243]
	s_waitcnt lgkmcnt(3)
	v_pk_add_f32 v[142:143], v[142:143], v[238:239]
	v_pk_add_f32 v[140:141], v[140:141], v[234:235]
	v_pk_add_f32 v[138:139], v[138:139], v[230:231]
	v_pk_add_f32 v[136:137], v[136:137], v[14:15]
	v_pk_add_f32 v[134:135], v[134:135], v[10:11]
	v_pk_add_f32 v[132:133], v[132:133], v[6:7]
	v_pk_add_f32 v[130:131], v[130:131], v[2:3]
	s_waitcnt lgkmcnt(0)
	v_pk_add_f32 v[128:129], v[128:129], v[244:245]
	v_pk_add_f32 v[126:127], v[126:127], v[240:241]
	v_pk_add_f32 v[124:125], v[124:125], v[236:237]
	v_pk_add_f32 v[122:123], v[122:123], v[232:233]
	v_pk_add_f32 v[120:121], v[120:121], v[228:229]
	v_pk_add_f32 v[118:119], v[118:119], v[12:13]
	v_pk_add_f32 v[116:117], v[116:117], v[8:9]
	v_pk_add_f32 v[114:115], v[114:115], v[4:5]
.LBB0_689:
	s_nop 0
	s_nop 9
	s_nop 0
	v_max3_f32 v0, v130, v131, v132
	v_max3_f32 v2, v114, v115, v116
	s_nop 0
	v_max3_f32 v0, v0, v133, v134
	v_max3_f32 v2, v2, v117, v118
	s_nop 0
	v_max3_f32 v0, v0, v135, v136
	v_max3_f32 v2, v2, v119, v120
	s_nop 0
	v_max3_f32 v0, v0, v137, v138
	v_max3_f32 v2, v2, v121, v122
	s_nop 0
	v_max3_f32 v0, v0, v139, v140
	v_max3_f32 v2, v2, v123, v124
	s_nop 0
	v_max3_f32 v0, v0, v141, v142
	v_max3_f32 v2, v2, v125, v126
	s_nop 0
	v_max3_f32 v0, v0, v143, v144
	v_max3_f32 v2, v2, v127, v128
	s_nop 0
	v_max3_f32 v0, v0, v2, v145
	s_nop 0
	v_max3_f32 v0, v0, v129, v129
	s_nop 0
	v_mov_b32_e32 v2, v0
	s_nop 1
	v_permlane32_swap_b32_e32 v0, v2
	v_max_f32_e32 v2, v2, v2
	v_max_f32_e32 v0, v0, v0
	v_max_f32_e32 v0, v0, v2
	v_cmp_lt_f32_e32 vcc, s36, v0
	s_cbranch_vccz .LBB0_682
	v_max_f32_e32 v0, v0, v0
	v_max_f32_e32 v0, 0, v0
	s_and_saveexec_b64 s[10:11], s[6:7]
	s_cbranch_execz .LBB0_681
	v_exp_f32_e64 v2, -v0
	ds_write_b32 v224, v2
	s_branch .LBB0_681

; __device__ __forceinline__ int crow(int r, int hi) { return (r & 3) + 8 * (r >> 2) + 4 * hi; }
; __device__ __forceinline__ void att_qs(bf16x8 (&pn)[4], f32x16 (&o)[4], f32x16& osum, f32x16& negm, const bf16x8 (&qf)[4], float& m_hat, ...
;     __builtin_amdgcn_s_setprio(1);
;     f32x16 c0, c1;
;     bf16x8 kf[4];
;     ...
;     kf[0] = ATT_KREAD(0); kf[1] = ATT_KREAD(1); kf[2] = ATT_KREAD(2); kf[3] = ATT_KREAD(3);
;     __builtin_amdgcn_sched_barrier(0);
; #pragma unroll
;     for (int i = 0; i < 8; ++i) {
;         if (i == 0) c0 = __builtin_amdgcn_mfma_f32_32x32x16_bf16(kf[0], qf[0], negm, 0, 0, 0);
;         else if (i == 1) c1 = __builtin_amdgcn_mfma_f32_32x32x16_bf16(kf[1], qf[0], negm, 0, 0, 0);
;         else if ((i & 1) == 0) c0 = __builtin_amdgcn_mfma_f32_32x32x16_bf16(kf[i & 3], qf[i >> 1], c0, 0, 0, 0);
;         else c1 = __builtin_amdgcn_mfma_f32_32x32x16_bf16(kf[i & 3], qf[i >> 1], c1, 0, 0, 0);
;         if (i + 4 < 8) kf[i & 3] = ATT_KREAD(i + 4);
;         __builtin_amdgcn_sched_barrier(0);
;     }
;     ...
;     if (near) {
; #pragma unroll
;         for (int r = 0; r < 16; ++r) { int i0 = lutbase + crow(r, hi), i1 = i0 + 32; i0 = i0 < 0 ? 0 : (i0 > 255 ? 255 : i0); i1 = i1 < 0 ? 0 : (i1 > 255 ? 255 : i1); c0[r] += lut[i0]; c1[r] += lut[i1]; }
.LBB0_702:
	s_add_i32 s9, s57, 0xffff8000
	s_and_b32 s58, s9, 0xc000
	s_cmp_le_u32 s56, s54
	s_cselect_b64 s[10:11], -1, 0
	s_cmp_gt_u32 s56, s54
	s_cbranch_scc1 .LBB0_710
	v_add_u32_e32 v14, s58, v177
	s_cmpk_lt_i32 s55, 0xffa6
	s_setprio 1
	ds_read_b128 v[2:5], v14
	ds_read_b128 v[6:9], v14 offset:512
	ds_read_b128 v[10:13], v14 offset:2048
	ds_read_b128 v[226:229], v14 offset:2560
	s_waitcnt lgkmcnt(3)
	v_mfma_f32_32x32x16_bf16 v[130:145], v[2:5], v[146:149], v[98:113]
	ds_read_b128 v[230:233], v14 offset:4096
	ds_read_b128 v[2:5], v14 offset:4608
	s_waitcnt lgkmcnt(4)
	v_mfma_f32_32x32x16_bf16 v[114:129], v[6:9], v[146:149], v[98:113]
	s_waitcnt lgkmcnt(3)
	v_mfma_f32_32x32x16_bf16 v[130:145], v[10:13], v[150:153], v[130:145]
	ds_read_b128 v[6:9], v14 offset:6144
	s_waitcnt lgkmcnt(3)
	v_mfma_f32_32x32x16_bf16 v[114:129], v[226:229], v[150:153], v[114:129]
	ds_read_b128 v[10:13], v14 offset:6656
	s_waitcnt lgkmcnt(3)
	v_mfma_f32_32x32x16_bf16 v[130:145], v[230:233], v[154:157], v[130:145]
	s_waitcnt lgkmcnt(2)
	v_mfma_f32_32x32x16_bf16 v[114:129], v[2:5], v[154:157], v[114:129]
	s_waitcnt lgkmcnt(1)
	v_mfma_f32_32x32x16_bf16 v[130:145], v[6:9], v[158:161], v[130:145]
	s_waitcnt lgkmcnt(0)
	v_mfma_f32_32x32x16_bf16 v[114:129], v[10:13], v[158:161], v[114:129]
	s_cbranch_scc1 .LBB0_705
	v_add_u32_e32 v17, s55, v219
	v_add_u32_e32 v2, 0x41, v17
	v_med3_i32 v3, v2, 0, v222
	v_med3_i32 v2, v2, s38, v223
	v_lshl_add_u32 v4, v2, 2, s37
	v_add_u32_e32 v2, 0x42, v17
	v_med3_i32 v5, v2, 0, v222
	v_med3_i32 v2, v2, s38, v223
	v_lshl_add_u32 v6, v2, 2, s37
	v_add_u32_e32 v2, 0x43, v17
	v_med3_i32 v7, v2, 0, v222
	v_med3_i32 v2, v2, s38, v223
	v_lshl_add_u32 v8, v2, 2, s37
	v_add_u32_e32 v2, 0x44, v17
	v_med3_i32 v9, v2, 0, v222
	v_med3_i32 v2, v2, s38, v223
	v_lshl_add_u32 v3, v3, 2, s37
	v_lshl_add_u32 v5, v5, 2, s37
	v_lshl_add_u32 v7, v7, 2, s37
	v_lshl_add_u32 v9, v9, 2, s37
	v_lshl_add_u32 v10, v2, 2, s37
	ds_read_b32 v2, v3
	ds_read_b32 v4, v4 offset:128
	ds_read_b32 v3, v5
	ds_read_b32 v5, v6 offset:128
	ds_read_b32 v6, v7
	ds_read_b32 v8, v8 offset:128
	ds_read_b32 v7, v9
	ds_read_b32 v9, v10 offset:128
	v_add_u32_e32 v10, 0x49, v17
	v_med3_i32 v11, v10, 0, v222
	v_med3_i32 v10, v10, s38, v223
	v_lshl_add_u32 v12, v10, 2, s37
	v_add_u32_e32 v10, 0x4a, v17
	v_med3_i32 v13, v10, 0, v222
	v_med3_i32 v10, v10, s38, v223
	v_lshl_add_u32 v14, v10, 2, s37
	v_add_u32_e32 v10, 0x4b, v17
	v_med3_i32 v15, v10, 0, v222
	v_med3_i32 v10, v10, s38, v223
	v_add_u32_e32 v229, 0x52, v17
	v_lshl_add_u32 v225, v10, 2, s37
	v_add_u32_e32 v10, 0x4c, v17
	v_med3_i32 v230, v229, 0, v222
	v_med3_i32 v229, v229, s38, v223
	v_med3_i32 v226, v10, 0, v222
	v_lshl_add_u32 v232, v229, 2, s37
	v_add_u32_e32 v229, 0x53, v17
	v_lshl_add_u32 v11, v11, 2, s37
	v_lshl_add_u32 v13, v13, 2, s37
	v_lshl_add_u32 v15, v15, 2, s37
	v_med3_i32 v10, v10, s38, v223
	v_lshl_add_u32 v227, v226, 2, s37
	v_lshl_add_u32 v231, v230, 2, s37
	v_med3_i32 v230, v229, 0, v222
	v_med3_i32 v229, v229, s38, v223
	v_lshl_add_u32 v228, v10, 2, s37
	ds_read_b32 v10, v11
	ds_read_b32 v12, v12 offset:128
	ds_read_b32 v11, v13
	ds_read_b32 v13, v14 offset:128
	ds_read_b32 v14, v15
	ds_read_b32 v226, v225 offset:128
	ds_read_b32 v15, v227
	ds_read_b32 v227, v228 offset:128
	v_add_u32_e32 v225, 0x51, v17
	v_lshl_add_u32 v234, v229, 2, s37
	v_add_u32_e32 v229, 0x54, v17
	v_add_u32_e32 v237, 0x5a, v17
	v_med3_i32 v228, v225, 0, v222
	v_med3_i32 v225, v225, s38, v223
	v_lshl_add_u32 v233, v230, 2, s37
	v_med3_i32 v230, v229, 0, v222
	v_med3_i32 v238, v237, 0, v222
	v_med3_i32 v237, v237, s38, v223
	v_lshl_add_u32 v228, v228, 2, s37
	v_lshl_add_u32 v225, v225, 2, s37
	v_med3_i32 v229, v229, s38, v223
	v_lshl_add_u32 v235, v230, 2, s37
	v_lshl_add_u32 v242, v237, 2, s37
	v_add_u32_e32 v237, 0x5b, v17
	v_lshl_add_u32 v236, v229, 2, s37
	ds_read_b32 v228, v228
	ds_read_b32 v230, v225 offset:128
	ds_read_b32 v229, v231
	ds_read_b32 v231, v232 offset:128
	ds_read_b32 v232, v233
	ds_read_b32 v234, v234 offset:128
	ds_read_b32 v233, v235
	ds_read_b32 v235, v236 offset:128
	v_add_u32_e32 v225, 0x59, v17
	v_lshl_add_u32 v239, v238, 2, s37
	v_med3_i32 v238, v237, 0, v222
	v_med3_i32 v237, v237, s38, v223
	v_add_u32_e32 v17, 0x5c, v17
	v_med3_i32 v236, v225, 0, v222
	v_lshl_add_u32 v243, v237, 2, s37
	v_med3_i32 v237, v17, 0, v222
	v_med3_i32 v225, v225, s38, v223
	v_lshl_add_u32 v236, v236, 2, s37
	v_lshl_add_u32 v240, v238, 2, s37
	v_med3_i32 v17, v17, s38, v223
	v_lshl_add_u32 v237, v237, 2, s37
	v_lshl_add_u32 v225, v225, 2, s37
	v_lshl_add_u32 v17, v17, 2, s37
	ds_read_b32 v236, v236
	ds_read_b32 v238, v225 offset:128
	ds_read_b32 v240, v240
	ds_read_b32 v241, v237
	ds_read_b32 v237, v239
	ds_read_b32 v239, v242 offset:128
	ds_read_b32 v242, v243 offset:128
	ds_read_b32 v243, v17 offset:128
	s_waitcnt lgkmcnt(4)
	v_pk_add_f32 v[144:145], v[144:145], v[240:241]
	s_waitcnt lgkmcnt(3)
	v_pk_add_f32 v[142:143], v[142:143], v[236:237]
	v_pk_add_f32 v[140:141], v[140:141], v[232:233]
	v_pk_add_f32 v[138:139], v[138:139], v[228:229]
	v_pk_add_f32 v[136:137], v[136:137], v[14:15]
	v_pk_add_f32 v[134:135], v[134:135], v[10:11]
	v_pk_add_f32 v[132:133], v[132:133], v[6:7]
	v_pk_add_f32 v[130:131], v[130:131], v[2:3]
	s_waitcnt lgkmcnt(0)
	v_pk_add_f32 v[128:129], v[128:129], v[242:243]
	v_pk_add_f32 v[126:127], v[126:127], v[238:239]
	v_pk_add_f32 v[124:125], v[124:125], v[234:235]
	v_pk_add_f32 v[122:123], v[122:123], v[230:231]
	v_pk_add_f32 v[120:121], v[120:121], v[226:227]
	v_pk_add_f32 v[118:119], v[118:119], v[12:13]
	v_pk_add_f32 v[116:117], v[116:117], v[8:9]
	v_pk_add_f32 v[114:115], v[114:115], v[4:5]
; __device__ __forceinline__ int crow(int r, int hi) { return (r & 3) + 8 * (r >> 2) + 4 * hi; }
; __device__ __forceinline__ float xhalf_max(float v) { auto rr = __builtin_amdgcn_permlane32_swap(__float_as_uint(v), __float_as_uint(v), false, false); return fmaxf(__uint_as_float(rr[0]), __uint_as_float(rr[1])); }
; __device__ __forceinline__ float max3a(float a, float b, float c) { float r; asm("v_max3_f32 %0, %1, %2, %3" : "=v"(r) : "v"(a), "v"(b), "v"(c)); return r; }
; __device__ __forceinline__ void att_qs(bf16x8 (&pn)[4], f32x16 (&o)[4], f32x16& osum, f32x16& negm, const bf16x8 (&qf)[4], float& m_hat, ...
;     ...
;     asm volatile("s_nop 15\n\ts_nop 7" : "+v"(c0), "+v"(c1));
;     float rm;
;     { float a = max3a(c0[0], c0[1], c0[2]), b = max3a(c1[0], c1[1], c1[2]);
; #pragma unroll
;       for (int r = 3; r < 15; r += 2) { a = max3a(a, c0[r], c0[r + 1]); b = max3a(b, c1[r], c1[r + 1]); }
;       rm = max3a(a, b, c0[15]); rm = max3a(rm, c1[15], c1[15]); }
;     rm = xhalf_max(rm);
;     if (first_tile) {
;         m_hat += rm;
; #pragma unroll
;         for (int r = 0; r < 16; ++r) { c0[r] -= rm; c1[r] -= rm; negm[r] = -m_hat; }
;     } else if (__any(rm > 8.0f)) {
;         const float dl = fmaxf(rm, 0.f); m_hat += dl; const float f = __builtin_amdgcn_exp2f(-dl);
; #pragma unroll
;         for (int r = 0; r < 16; ++r) { c0[r] -= dl; c1[r] -= dl; negm[r] = -m_hat; }
;         if (hi == 0) scr[i32] = f;
;         asm volatile("s_waitcnt lgkmcnt(0)" ::: "memory");
; #pragma unroll
;         for (int r = 0; r < 16; ++r) { const float fr_ = scr[crow(r, hi)]; osum[r] *= fr_;
; #pragma unroll
;             for (int d = 0; d < 4; ++d) o[d][r] *= fr_; }
;     }
.LBB0_705:
	s_nop 0
	s_nop 9
	s_nop 0
	v_max3_f32 v2, v130, v131, v132
	v_max3_f32 v3, v114, v115, v116
	s_nop 0
	v_max3_f32 v2, v2, v133, v134
	v_max3_f32 v3, v3, v117, v118
	s_nop 0
	v_max3_f32 v2, v2, v135, v136
	v_max3_f32 v3, v3, v119, v120
	s_nop 0
	v_max3_f32 v2, v2, v137, v138
	v_max3_f32 v3, v3, v121, v122
	s_nop 0
	v_max3_f32 v2, v2, v139, v140
	v_max3_f32 v3, v3, v123, v124
	s_nop 0
	v_max3_f32 v2, v2, v141, v142
	v_max3_f32 v3, v3, v125, v126
	s_nop 0
	v_max3_f32 v2, v2, v143, v144
	v_max3_f32 v3, v3, v127, v128
	s_nop 0
	v_max3_f32 v2, v2, v3, v145
	s_nop 0
	v_max3_f32 v2, v2, v129, v129
	s_nop 0
	v_mov_b32_e32 v3, v2
	s_nop 1
	v_permlane32_swap_b32_e32 v2, v3
	v_max_f32_e32 v3, v3, v3
	v_max_f32_e32 v2, v2, v2
	v_max_f32_e32 v2, v2, v3
	v_cmp_lt_f32_e32 vcc, s36, v2
	s_cbranch_vccz .LBB0_709
	v_max_f32_e32 v2, v2, v2
	v_max_f32_e32 v2, 0, v2
	s_and_saveexec_b64 s[28:29], s[6:7]
	v_exp_f32_e64 v3, -v2
	ds_write_b32 v224, v3
	s_or_b64 exec, exec, s[28:29]
	s_waitcnt lgkmcnt(0)
	v_add_u32_e32 v3, s51, v187
	ds_read_b128 v[4:7], v3 offset:64
	ds_read_b128 v[8:11], v3 offset:96
	ds_read_b128 v[12:15], v3
	ds_read_b128 v[98:101], v3 offset:32
	v_add_f32_e32 v0, v0, v2
	v_xor_b32_e32 v113, 0x80000000, v0
	v_sub_f32_e32 v144, v144, v2
	v_sub_f32_e32 v145, v145, v2
	v_sub_f32_e32 v142, v142, v2
	v_sub_f32_e32 v143, v143, v2
	v_sub_f32_e32 v140, v140, v2
	v_sub_f32_e32 v141, v141, v2
	v_sub_f32_e32 v138, v138, v2
	v_sub_f32_e32 v139, v139, v2
	v_sub_f32_e32 v136, v136, v2
	v_sub_f32_e32 v137, v137, v2
	v_sub_f32_e32 v134, v134, v2
	v_sub_f32_e32 v135, v135, v2
	v_sub_f32_e32 v132, v132, v2
	v_sub_f32_e32 v133, v133, v2
	v_sub_f32_e32 v130, v130, v2
	v_sub_f32_e32 v131, v131, v2
	v_sub_f32_e32 v129, v129, v2
	v_sub_f32_e32 v128, v128, v2
	v_sub_f32_e32 v127, v127, v2
	v_sub_f32_e32 v126, v126, v2
	v_sub_f32_e32 v124, v124, v2
	v_sub_f32_e32 v125, v125, v2
	v_sub_f32_e32 v122, v122, v2
	v_sub_f32_e32 v123, v123, v2
	v_sub_f32_e32 v120, v120, v2
	v_sub_f32_e32 v121, v121, v2
	v_sub_f32_e32 v118, v118, v2
	v_sub_f32_e32 v119, v119, v2
	v_sub_f32_e32 v116, v116, v2
	v_sub_f32_e32 v117, v117, v2
	v_sub_f32_e32 v114, v114, v2
	v_sub_f32_e32 v115, v115, v2
	s_waitcnt lgkmcnt(2)
	v_pk_mul_f32 v[30:31], v[30:31], v[8:9]
	v_pk_mul_f32 v[26:27], v[26:27], v[4:5]
	s_waitcnt lgkmcnt(0)
	v_pk_mul_f32 v[22:23], v[22:23], v[98:99]
	v_pk_mul_f32 v[32:33], v[32:33], v[10:11]
	v_pk_mul_f32 v[28:29], v[28:29], v[6:7]
	v_pk_mul_f32 v[24:25], v[24:25], v[100:101]
	v_pk_mul_f32 v[20:21], v[20:21], v[14:15]
	v_pk_mul_f32 v[18:19], v[18:19], v[12:13]
	v_pk_mul_f32 v[46:47], v[46:47], v[8:9]
	v_pk_mul_f32 v[42:43], v[42:43], v[4:5]
	v_pk_mul_f32 v[38:39], v[38:39], v[98:99]
	v_pk_mul_f32 v[48:49], v[48:49], v[10:11]
	v_pk_mul_f32 v[44:45], v[44:45], v[6:7]
	v_pk_mul_f32 v[40:41], v[40:41], v[100:101]
	v_pk_mul_f32 v[36:37], v[36:37], v[14:15]
	v_pk_mul_f32 v[34:35], v[34:35], v[12:13]
	v_pk_mul_f32 v[62:63], v[62:63], v[8:9]
	v_pk_mul_f32 v[58:59], v[58:59], v[4:5]
	v_pk_mul_f32 v[54:55], v[54:55], v[98:99]
	v_pk_mul_f32 v[64:65], v[64:65], v[10:11]
	v_pk_mul_f32 v[60:61], v[60:61], v[6:7]
	v_pk_mul_f32 v[56:57], v[56:57], v[100:101]
	v_pk_mul_f32 v[52:53], v[52:53], v[14:15]
	v_pk_mul_f32 v[50:51], v[50:51], v[12:13]
	v_pk_mul_f32 v[78:79], v[78:79], v[8:9]
	v_pk_mul_f32 v[74:75], v[74:75], v[4:5]
	v_pk_mul_f32 v[70:71], v[70:71], v[98:99]
	v_pk_mul_f32 v[80:81], v[80:81], v[10:11]
	v_pk_mul_f32 v[76:77], v[76:77], v[6:7]
	v_pk_mul_f32 v[72:73], v[72:73], v[100:101]
	v_pk_mul_f32 v[68:69], v[68:69], v[14:15]
	v_pk_mul_f32 v[66:67], v[66:67], v[12:13]
	v_pk_mul_f32 v[94:95], v[94:95], v[8:9]
	v_pk_mul_f32 v[90:91], v[90:91], v[4:5]
	v_pk_mul_f32 v[86:87], v[86:87], v[98:99]
	v_pk_mul_f32 v[96:97], v[96:97], v[10:11]
	v_pk_mul_f32 v[92:93], v[92:93], v[6:7]
	v_pk_mul_f32 v[88:89], v[88:89], v[100:101]
	v_pk_mul_f32 v[84:85], v[84:85], v[14:15]
	v_pk_mul_f32 v[82:83], v[82:83], v[12:13]
	v_mov_b32_e32 v112, v113
	v_mov_b32_e32 v111, v113
	v_mov_b32_e32 v110, v113
	v_mov_b32_e32 v109, v113
	v_mov_b32_e32 v108, v113
	v_mov_b32_e32 v107, v113
	v_mov_b32_e32 v106, v113
	v_mov_b32_e32 v105, v113
	v_mov_b32_e32 v104, v113
	v_mov_b32_e32 v103, v113
	v_mov_b32_e32 v102, v113
	v_mov_b32_e32 v101, v113
	v_mov_b32_e32 v100, v113
	v_mov_b32_e32 v99, v113
	v_mov_b32_e32 v98, v113

; #define LAS __attribute__((address_space(3)))
; #define ATT_VREADK(ks) do { _Pragma("unroll") for (int d_ = 0; d_ < 4; ++d_) { vl[(ks) & 1][d_] = vtr(vb + d_ * 4096 + (ks) * 1024); vh[(ks) & 1][d_] = vtr(vb + d_ * 4096 + (ks) * 1024 + 512); } } while (0)
; __device__ __forceinline__ void att_pv(const bf16x8 (&pp)[4], f32x16 (&o)[4], f32x16& osum, const LAS unsigned char* vb) {
;     s16x4 vl[2][4], vh[2][4];
;     ...
;     const bf16x8 ones = (bf16x8){0x3F80, 0x3F80, 0x3F80, 0x3F80, 0x3F80, 0x3F80, 0x3F80, 0x3F80};
;     ATT_VREADK(0);
; #pragma unroll
;     for (int ks = 0; ks < 4; ++ks) {
;         if (ks + 1 < 4) ATT_VREADK(ks + 1);
;         osum = __builtin_amdgcn_mfma_f32_32x32x16_bf16(pp[ks], ones, osum, 0, 0, 0);
; #pragma unroll
;         for (int d = 0; d < 4; ++d) { const int bk = ks & 1;
;             const bf16x8 vf = (bf16x8){vl[bk][d][0], vl[bk][d][1], vl[bk][d][2], vl[bk][d][3], vh[bk][d][0], vh[bk][d][1], vh[bk][d][2], vh[bk][d][3]};
;             o[d] = __builtin_amdgcn_mfma_f32_32x32x16_bf16(pp[ks], vf, o[d], 0, 0, 0); }
;     }
.LBB0_710:
	s_add_i32 s9, s56, 2
	s_min_u32 s16, s9, s52
	s_and_b32 s9, s57, 0xc000
	s_lshl_b64 s[28:29], s[16:17], 14
	s_or_b32 s9, s9, s53
	s_add_i32 s9, s9, 0
	v_lshl_add_u64 v[14:15], v[178:179], 0, s[28:29]
	s_mov_b32 m0, s9
	s_nop 0
	global_load_lds_dwordx4 v[14:15], off
	v_lshl_add_u64 v[14:15], v[14:15], 0, s[22:23]
	s_add_i32 s59, s9, 0x2000
	s_mov_b32 m0, s59
	s_nop 0
	global_load_lds_dwordx4 v[14:15], off
	s_add_i32 s16, s9, 0x10000
	v_lshl_add_u64 v[14:15], v[180:181], 0, s[28:29]
	s_mov_b32 m0, s16
	s_nop 0
	global_load_lds_dwordx4 v[14:15], off
	v_lshl_add_u64 v[14:15], v[14:15], 0, s[22:23]
	s_add_i32 s9, s9, 0x12000
	s_andn2_b64 vcc, exec, s[10:11]
	s_mov_b32 m0, s9
	s_nop 0
	global_load_lds_dwordx4 v[14:15], off
	s_cbranch_vccnz .LBB0_701
	v_add_u32_e32 v14, s58, v185
	ds_read_b64_tr_b16 v[122:123], v14
	ds_read_b64_tr_b16 v[124:125], v14 offset:512
	ds_read_b64_tr_b16 v[126:127], v14 offset:1024
	ds_read_b64_tr_b16 v[128:129], v14 offset:1536
	s_mov_b32 s10, s8
	s_mov_b32 s11, s8
	s_waitcnt lgkmcnt(2)
	v_mfma_f32_32x32x16_bf16 v[34:49], v[114:117], v[122:125], v[34:49]
	ds_read_b64_tr_b16 v[122:123], v14 offset:4096
	ds_read_b64_tr_b16 v[124:125], v14 offset:4608
	ds_read_b64_tr_b16 v[130:131], v14 offset:5120
	ds_read_b64_tr_b16 v[132:133], v14 offset:5632
	s_mov_b32 s9, s8
	v_mov_b64_e32 v[120:121], s[10:11]
	v_mov_b64_e32 v[118:119], s[8:9]
	s_waitcnt lgkmcnt(2)
	v_mfma_f32_32x32x16_bf16 v[50:65], v[114:117], v[122:125], v[50:65]
	ds_read_b64_tr_b16 v[122:123], v14 offset:8192
	ds_read_b64_tr_b16 v[124:125], v14 offset:8704
	ds_read_b64_tr_b16 v[134:135], v14 offset:9216
	ds_read_b64_tr_b16 v[136:137], v14 offset:9728
	s_waitcnt lgkmcnt(2)
	v_mfma_f32_32x32x16_bf16 v[66:81], v[114:117], v[122:125], v[66:81]
	ds_read_b64_tr_b16 v[122:123], v14 offset:12288
	ds_read_b64_tr_b16 v[124:125], v14 offset:12800
	ds_read_b64_tr_b16 v[138:139], v14 offset:13312
	ds_read_b64_tr_b16 v[140:141], v14 offset:13824
	v_mfma_f32_32x32x16_bf16 v[34:49], v[10:13], v[126:129], v[34:49]
	v_mfma_f32_32x32x16_bf16 v[18:33], v[114:117], v[118:121], v[18:33]
	s_waitcnt lgkmcnt(2)
	v_mfma_f32_32x32x16_bf16 v[82:97], v[114:117], v[122:125], v[82:97]
	ds_read_b64_tr_b16 v[122:123], v14 offset:2048
	ds_read_b64_tr_b16 v[124:125], v14 offset:2560
	ds_read_b64_tr_b16 v[126:127], v14 offset:3072
	ds_read_b64_tr_b16 v[128:129], v14 offset:3584
	v_mfma_f32_32x32x16_bf16 v[50:65], v[10:13], v[130:133], v[50:65]
	v_mfma_f32_32x32x16_bf16 v[66:81], v[10:13], v[134:137], v[66:81]
	s_waitcnt lgkmcnt(2)
	v_mfma_f32_32x32x16_bf16 v[34:49], v[6:9], v[122:125], v[34:49]
	ds_read_b64_tr_b16 v[122:123], v14 offset:6144
	ds_read_b64_tr_b16 v[124:125], v14 offset:6656
	ds_read_b64_tr_b16 v[130:131], v14 offset:7168
	ds_read_b64_tr_b16 v[132:133], v14 offset:7680
	v_mfma_f32_32x32x16_bf16 v[18:33], v[10:13], v[118:121], v[18:33]
	v_mfma_f32_32x32x16_bf16 v[82:97], v[10:13], v[138:141], v[82:97]
	s_waitcnt lgkmcnt(2)
	v_mfma_f32_32x32x16_bf16 v[50:65], v[6:9], v[122:125], v[50:65]
	ds_read_b64_tr_b16 v[122:123], v14 offset:10240
	ds_read_b64_tr_b16 v[124:125], v14 offset:10752
	ds_read_b64_tr_b16 v[134:135], v14 offset:11264
	ds_read_b64_tr_b16 v[136:137], v14 offset:11776
	s_waitcnt lgkmcnt(2)
	v_mfma_f32_32x32x16_bf16 v[66:81], v[6:9], v[122:125], v[66:81]
	ds_read_b64_tr_b16 v[122:123], v14 offset:14336
	ds_read_b64_tr_b16 v[124:125], v14 offset:14848
	ds_read_b64_tr_b16 v[138:139], v14 offset:15360
	ds_read_b64_tr_b16 v[140:141], v14 offset:15872
	v_mfma_f32_32x32x16_bf16 v[18:33], v[6:9], v[118:121], v[18:33]
	s_waitcnt lgkmcnt(2)
	v_mfma_f32_32x32x16_bf16 v[82:97], v[6:9], v[122:125], v[82:97]
	v_mfma_f32_32x32x16_bf16 v[18:33], v[2:5], v[118:121], v[18:33]
	v_mfma_f32_32x32x16_bf16 v[34:49], v[2:5], v[126:129], v[34:49]
	v_mfma_f32_32x32x16_bf16 v[50:65], v[2:5], v[130:133], v[50:65]
	v_mfma_f32_32x32x16_bf16 v[66:81], v[2:5], v[134:137], v[66:81]
	s_waitcnt lgkmcnt(0)
	v_mfma_f32_32x32x16_bf16 v[82:97], v[2:5], v[138:141], v[82:97]
	s_branch .LBB0_701
